# mem-attention loop: software-pipelined K-tile prefetch into spare VGPRs v240-255 (was load-then-wait each iteration); nop-padded kernel ends
# baseline (speedup 1.0000x reference)
; DI void mem_tile(const KFrag& kf, const VFrag& vf, const bf16x8 (&qf)[4], float& mx, float& lsum, f32x16& m0, f32x16& m1) {
;     const f32x16 st = qk_mma(kf, qf);
;     float tm = st[0];
; #pragma unroll
;     for (int i = 1; i < 16; ++i) tm = __builtin_fmaxf(tm, st[i]);
;     tm = __builtin_fmaxf(tm, __shfl_xor(tm, 32));
;     const float nm = __builtin_fmaxf(mx, tm), alpha = __builtin_amdgcn_exp2f(mx - nm); mx = nm;
; DI void mixer_phase(const Params& p, unsigned char* ldsraw, int vid) {
;     ...
;             if (wid < 4) {
;                 bf16x8 qfA[4], qfB[4];
;                 { const bf16_t* qp = RR + (size_t)tqA * 2048 + 768 + 64 * wid + 8 * hh;
; #pragma unroll
;                   for (int s = 0; s < 4; ++s) { qfA[s] = *(const bf16x8*)(qp + 16 * s); qfB[s] = *(const bf16x8*)(qp + 32 * 2048 + 16 * s); } }
;                 const bf16_t* kb = MK + (size_t)pr * 256 + 64 * wid + 8 * hh;
;                 const bf16_t* vb = MVT + (size_t)(64 * wid + r) * 256 + 8 * hh;
;                 float mxA = -1e30f, lsA = 0.f, mxB = -1e30f, lsB = 0.f;
;                 KFrag kc, kn; VFrag vc, vn;
;                 load_k(kc, kb); load_v(vc, vb, 256);
; #pragma unroll 1
;                 for (int mt = 0; mt < 8; ++mt) {
;                     const int nx = mt < 7 ? mt + 1 : 7;
;                     load_k(kn, kb + (size_t)(32 * nx) * 256); load_v(vn, vb + 32 * nx, 256);
;                     mem_tile(kc, vc, qfA, mxA, lsA, a0, a1);
;                     mem_tile(kc, vc, qfB, mxB, lsB, b0, b1);
;                     kc = kn; vc = vn;
;                 }
.LBB0_432:
	s_and_b64 vcc, exec, s[0:1]
	s_cbranch_vccz .LBB0_438
	v_lshlrev_b32_e32 v0, 1, v206
	s_waitcnt lgkmcnt(0)
	v_lshrrev_b32_e32 v1, 1, v205
	v_and_b32_e32 v0, 8, v0
	v_and_b32_e32 v1, 4, v1
	v_and_b32_e32 v2, 19, v205
	v_or3_b32 v6, v2, v0, v1
	v_lshlrev_b64 v[0:1], 12, v[96:97]
	v_ashrrev_i32_e32 v183, 31, v182
	v_lshl_add_u64 v[0:1], s[82:83], 0, v[0:1]
	v_lshlrev_b64 v[2:3], 1, v[182:183]
	v_lshl_add_u64 v[0:1], v[0:1], 0, v[2:3]
	v_add_co_u32_e32 v4, vcc, 0x20000, v0
	v_lshlrev_b32_e32 v176, 9, v6
	s_nop 0
	v_addc_co_u32_e32 v5, vcc, 0, v1, vcc
	global_load_dwordx4 v[96:99], v[0:1], off offset:1536
	global_load_dwordx4 v[100:103], v[0:1], off offset:1568
	global_load_dwordx4 v[104:107], v[4:5], off offset:1536
	global_load_dwordx4 v[108:111], v[4:5], off offset:1568
	global_load_dwordx4 v[112:115], v[0:1], off offset:1600
	global_load_dwordx4 v[116:119], v[0:1], off offset:1632
	global_load_dwordx4 v[120:123], v[4:5], off offset:1600
	global_load_dwordx4 v[124:127], v[4:5], off offset:1632
	v_lshl_add_u64 v[0:1], s[78:79], 0, v[176:177]
	v_lshl_add_u64 v[148:149], v[0:1], 0, v[2:3]
	v_or_b32_e32 v0, s74, v206
	v_ashrrev_i32_e32 v1, 31, v0
	v_lshlrev_b64 v[0:1], 9, v[0:1]
	v_lshl_add_u64 v[0:1], s[46:47], 0, v[0:1]
	v_lshl_add_u64 v[150:151], v[0:1], 0, v[2:3]
	v_mov_b32_e32 v0, 0
	v_mov_b32_e32 v147, 0xf149f2ca
	s_mov_b32 s0, 32
	v_mov_b64_e32 v[154:155], v[150:151]
	v_mov_b64_e32 v[156:157], v[148:149]
	global_load_dwordx4 v[240:243], v[148:149], off
	global_load_dwordx4 v[244:247], v[148:149], off offset:32
	global_load_dwordx4 v[248:251], v[148:149], off offset:64
	global_load_dwordx4 v[252:255], v[148:149], off offset:96
	v_mov_b32_e32 v165, 0xf149f2ca
	v_mov_b32_e32 v1, v0
	v_mov_b32_e32 v2, v0
	v_mov_b32_e32 v3, v0
	v_mov_b32_e32 v4, v0
	v_mov_b32_e32 v5, v0
	v_mov_b32_e32 v6, v0
	v_mov_b32_e32 v7, v0
	v_mov_b32_e32 v8, v0
	v_mov_b32_e32 v9, v0
	v_mov_b32_e32 v10, v0
	v_mov_b32_e32 v11, v0
	v_mov_b32_e32 v12, v0
	v_mov_b32_e32 v13, v0
	v_mov_b32_e32 v14, v0
	v_mov_b32_e32 v15, v0
	v_mov_b32_e32 v16, v0
	v_mov_b32_e32 v17, v0
	v_mov_b32_e32 v18, v0
	v_mov_b32_e32 v19, v0
	v_mov_b32_e32 v20, v0
	v_mov_b32_e32 v21, v0
	v_mov_b32_e32 v22, v0
	v_mov_b32_e32 v23, v0
	v_mov_b32_e32 v24, v0
	v_mov_b32_e32 v25, v0
	v_mov_b32_e32 v26, v0
	v_mov_b32_e32 v27, v0
	v_mov_b32_e32 v28, v0
	v_mov_b32_e32 v29, v0
	v_mov_b32_e32 v30, v0
	v_mov_b32_e32 v31, v0
	v_mov_b32_e32 v32, v0
	v_mov_b32_e32 v33, v0
	v_mov_b32_e32 v34, v0
	v_mov_b32_e32 v35, v0
	v_mov_b32_e32 v36, v0
	v_mov_b32_e32 v37, v0
	v_mov_b32_e32 v38, v0
	v_mov_b32_e32 v39, v0
	v_mov_b32_e32 v40, v0
	v_mov_b32_e32 v41, v0
	v_mov_b32_e32 v42, v0
	v_mov_b32_e32 v43, v0
	v_mov_b32_e32 v44, v0
	v_mov_b32_e32 v45, v0
	v_mov_b32_e32 v46, v0
	v_mov_b32_e32 v47, v0
	v_mov_b32_e32 v48, v0
	v_mov_b32_e32 v49, v0
	v_mov_b32_e32 v50, v0
	v_mov_b32_e32 v51, v0
	v_mov_b32_e32 v52, v0
	v_mov_b32_e32 v53, v0
	v_mov_b32_e32 v54, v0
	v_mov_b32_e32 v55, v0
	v_mov_b32_e32 v56, v0
	v_mov_b32_e32 v57, v0
	v_mov_b32_e32 v58, v0
	v_mov_b32_e32 v59, v0
	v_mov_b32_e32 v60, v0
	v_mov_b32_e32 v61, v0
	v_mov_b32_e32 v62, v0
	v_mov_b32_e32 v63, v0
	v_mov_b32_e32 v152, v0
	v_mov_b32_e32 v153, v0
.LBB0_434:
	s_waitcnt vmcnt(0)
	v_mov_b64_e32 v[64:65], v[240:241]
	v_mov_b64_e32 v[66:67], v[242:243]
	v_mov_b64_e32 v[128:129], v[244:245]
	v_mov_b64_e32 v[130:131], v[246:247]
	v_mov_b64_e32 v[132:133], v[248:249]
	v_mov_b64_e32 v[134:135], v[250:251]
	v_mov_b64_e32 v[136:137], v[252:253]
	v_mov_b64_e32 v[138:139], v[254:255]
	s_movk_i32 s1, 0x4000
	s_cmpk_lg_i32 s0, 0x100
	s_cselect_b32 s72, s0, 0xe0
	s_add_i32 s0, s0, 32
	s_lshl_b64 s[8:9], s[72:73], 9
	v_lshl_add_u64 v[156:157], v[148:149], 0, s[8:9]
	s_cmpk_eq_i32 s0, 0x120
	global_load_dwordx4 v[240:243], v[156:157], off
	global_load_dwordx4 v[244:247], v[156:157], off offset:32
	global_load_dwordx4 v[248:251], v[156:157], off offset:64
	global_load_dwordx4 v[252:255], v[156:157], off offset:96
	v_mfma_f32_32x32x16_bf16 v[80:95], v[64:67], v[96:99], 0
	v_mfma_f32_32x32x16_bf16 v[64:79], v[64:67], v[104:107], 0
	v_mfma_f32_32x32x16_bf16 v[80:95], v[128:131], v[100:103], v[80:95]
	v_mfma_f32_32x32x16_bf16 v[64:79], v[128:131], v[108:111], v[64:79]
	global_load_dwordx4 v[128:131], v[154:155], off offset:32
	v_mfma_f32_32x32x16_bf16 v[80:95], v[132:135], v[112:115], v[80:95]
	v_mfma_f32_32x32x16_bf16 v[64:79], v[132:135], v[120:123], v[64:79]
	global_load_dwordx4 v[132:135], v[154:155], off
	v_add_co_u32_e32 v154, vcc, s1, v154
	s_nop 1
	v_addc_co_u32_e32 v155, vcc, 0, v155, vcc
	global_load_dwordx4 v[166:169], v[154:155], off offset:32
	global_load_dwordx4 v[170:173], v[154:155], off
	v_mfma_f32_32x32x16_bf16 v[80:95], v[136:139], v[116:119], v[80:95]
	v_lshl_add_u64 v[154:155], s[72:73], 1, v[150:151]
	v_mfma_f32_32x32x16_bf16 v[64:79], v[136:139], v[124:127], v[64:79]
	s_nop 9
	v_max_f32_e32 v136, v81, v81
	v_max_f32_e32 v137, v80, v80
	v_max_f32_e32 v136, v137, v136
	v_max3_f32 v136, v136, v82, v83
	v_max3_f32 v136, v136, v84, v85
	v_max3_f32 v136, v136, v86, v87
	v_max3_f32 v136, v136, v88, v89
	v_max_f32_e32 v138, v65, v65
	v_max_f32_e32 v139, v64, v64
	v_max_f32_e32 v137, v139, v138
	v_max3_f32 v137, v137, v66, v67
	v_max3_f32 v137, v137, v68, v69
	v_max3_f32 v137, v137, v70, v71
	v_max3_f32 v137, v137, v72, v73
	v_max3_f32 v136, v136, v90, v91
	v_max3_f32 v137, v137, v74, v75
	v_max3_f32 v136, v136, v92, v93
	v_max3_f32 v137, v137, v76, v77
	v_max3_f32 v136, v136, v94, v95
	v_max3_f32 v137, v137, v78, v79
	ds_bpermute_b32 v138, v181, v136
	ds_bpermute_b32 v139, v181, v137
	s_waitcnt lgkmcnt(1)
	v_max3_f32 v136, v165, v136, v138
	s_waitcnt lgkmcnt(0)
; #define MFMA32(a, b, c) __builtin_amdgcn_mfma_f32_32x32x16_bf16((a), (b), (c), 0, 0, 0)
; DI void pv_mma(const VFrag& f, const f32x16& w, f32x16& o0, f32x16& o1) {
; #pragma unroll
;     for (int s = 0; s < 2; ++s) { const bf16x8 pf = pack8(w, s); o0 = MFMA32(f.v[0][s], pf, o0); o1 = MFMA32(f.v[1][s], pf, o1); }
; }
; DI void mem_tile(const KFrag& kf, const VFrag& vf, const bf16x8 (&qf)[4], float& mx, float& lsum, f32x16& m0, f32x16& m1) {
;     const f32x16 st = qk_mma(kf, qf);
;     float tm = st[0];
; #pragma unroll
;     for (int i = 1; i < 16; ++i) tm = __builtin_fmaxf(tm, st[i]);
;     tm = __builtin_fmaxf(tm, __shfl_xor(tm, 32));
;     const float nm = __builtin_fmaxf(mx, tm), alpha = __builtin_amdgcn_exp2f(mx - nm); mx = nm;
;     f32x16 w; float ps = 0.f;
; #pragma unroll
;     for (int i = 0; i < 16; ++i) { w[i] = __builtin_amdgcn_exp2f(st[i] - nm); ps += w[i]; }
;     lsum = lsum * alpha + ps;
; #pragma unroll
;     for (int i = 0; i < 16; ++i) { m0[i] *= alpha; m1[i] *= alpha; }
;     pv_mma(vf, w, m0, m1);
; }
	v_max3_f32 v137, v147, v137, v139
	v_sub_f32_e32 v139, v165, v136
	v_sub_f32_e32 v80, v80, v136
	v_sub_f32_e32 v81, v81, v136
	v_sub_f32_e32 v82, v82, v136
	v_sub_f32_e32 v83, v83, v136
	v_sub_f32_e32 v84, v84, v136
	v_sub_f32_e32 v85, v85, v136
	v_sub_f32_e32 v86, v86, v136
	v_sub_f32_e32 v87, v87, v136
	v_sub_f32_e32 v174, v92, v136
	v_sub_f32_e32 v175, v147, v137
	v_sub_f32_e32 v88, v88, v136
	v_sub_f32_e32 v89, v89, v136
	v_sub_f32_e32 v138, v90, v136
	v_sub_f32_e32 v91, v91, v136
	v_sub_f32_e32 v93, v93, v136
	v_sub_f32_e32 v182, v94, v136
	v_sub_f32_e32 v95, v95, v136
	v_sub_f32_e32 v64, v64, v137
	v_sub_f32_e32 v65, v65, v137
	v_sub_f32_e32 v66, v66, v137
	v_sub_f32_e32 v67, v67, v137
	v_sub_f32_e32 v68, v68, v137
	v_sub_f32_e32 v69, v69, v137
	v_sub_f32_e32 v70, v70, v137
	v_sub_f32_e32 v71, v71, v137
	v_sub_f32_e32 v183, v72, v137
	v_sub_f32_e32 v185, v74, v137
	v_sub_f32_e32 v187, v76, v137
	v_sub_f32_e32 v189, v78, v137
	v_mov_b32_e32 v165, v136
	v_exp_f32_e32 v72, v80
	v_exp_f32_e32 v74, v81
	v_exp_f32_e32 v76, v82
	v_exp_f32_e32 v78, v83
	v_exp_f32_e32 v80, v84
	v_exp_f32_e32 v82, v85
	v_exp_f32_e32 v84, v86
	v_exp_f32_e32 v86, v87
	v_exp_f32_e32 v136, v174
	v_exp_f32_e32 v174, v139
	v_exp_f32_e32 v175, v175
	v_sub_f32_e32 v184, v73, v137
	v_sub_f32_e32 v186, v75, v137
	v_sub_f32_e32 v188, v77, v137
	v_sub_f32_e32 v190, v79, v137
	v_exp_f32_e32 v73, v64
	v_exp_f32_e32 v75, v65
	v_exp_f32_e32 v77, v66
	v_exp_f32_e32 v79, v67
	v_exp_f32_e32 v81, v68
	v_exp_f32_e32 v83, v69
	v_exp_f32_e32 v85, v70
	v_exp_f32_e32 v87, v71
	v_cvt_pk_bf16_f32 v64, v72, v74
	v_cvt_pk_bf16_f32 v65, v76, v78
	v_cvt_pk_bf16_f32 v66, v80, v82
	v_pk_mul_f32 v[62:63], v[62:63], v[174:175] op_sel_hi:[1,0]
	v_pk_mul_f32 v[60:61], v[60:61], v[174:175] op_sel_hi:[1,0]
	v_pk_mul_f32 v[58:59], v[58:59], v[174:175] op_sel_hi:[1,0]
	v_pk_mul_f32 v[56:57], v[56:57], v[174:175] op_sel_hi:[1,0]
	v_pk_mul_f32 v[54:55], v[54:55], v[174:175] op_sel_hi:[1,0]
	v_pk_mul_f32 v[52:53], v[52:53], v[174:175] op_sel_hi:[1,0]
	v_pk_mul_f32 v[50:51], v[50:51], v[174:175] op_sel_hi:[1,0]
	v_pk_mul_f32 v[48:49], v[48:49], v[174:175] op_sel_hi:[1,0]
	v_pk_mul_f32 v[46:47], v[46:47], v[174:175] op_sel_hi:[1,0]
	v_pk_mul_f32 v[44:45], v[44:45], v[174:175] op_sel_hi:[1,0]
	v_pk_mul_f32 v[42:43], v[42:43], v[174:175] op_sel_hi:[1,0]
	v_pk_mul_f32 v[40:41], v[40:41], v[174:175] op_sel_hi:[1,0]
	v_pk_mul_f32 v[38:39], v[38:39], v[174:175] op_sel_hi:[1,0]
	v_pk_mul_f32 v[36:37], v[36:37], v[174:175] op_sel_hi:[1,0]
	v_cvt_pk_bf16_f32 v67, v84, v86
	v_pk_mul_f32 v[34:35], v[34:35], v[174:175] op_sel_hi:[1,0]
	v_pk_mul_f32 v[32:33], v[32:33], v[174:175] op_sel_hi:[1,0]
	v_mov_b32_e32 v176, v175
	s_waitcnt vmcnt(2)
	v_mfma_f32_32x32x16_bf16 v[48:63], v[132:135], v[64:67], v[48:63]
	v_cvt_pk_bf16_f32 v68, v73, v75
	v_cvt_pk_bf16_f32 v69, v77, v79
	v_cvt_pk_bf16_f32 v70, v81, v83
	v_cvt_pk_bf16_f32 v71, v85, v87
	v_mul_f32_e64 v30, v30, v176
	v_mul_f32_e64 v31, v31, v176
	v_pk_mul_f32 v[28:29], v[28:29], v[176:177] op_sel_hi:[1,0]
	v_pk_mul_f32 v[26:27], v[26:27], v[176:177] op_sel_hi:[1,0]
	s_waitcnt vmcnt(0)
	v_mfma_f32_32x32x16_bf16 v[32:47], v[170:173], v[64:67], v[32:47]
	v_mul_f32_e64 v24, v24, v176
	v_mul_f32_e64 v25, v25, v176
	v_mul_f32_e64 v22, v22, v176
	v_mul_f32_e64 v23, v23, v176
	v_mul_f32_e64 v20, v20, v176
	v_mul_f32_e64 v21, v21, v176
	v_pk_mul_f32 v[18:19], v[18:19], v[176:177] op_sel_hi:[1,0]
	v_pk_mul_f32 v[16:17], v[16:17], v[176:177] op_sel_hi:[1,0]
	v_pk_mul_f32 v[14:15], v[14:15], v[176:177] op_sel_hi:[1,0]
	v_pk_mul_f32 v[12:13], v[12:13], v[176:177] op_sel_hi:[1,0]
	v_pk_mul_f32 v[10:11], v[10:11], v[176:177] op_sel_hi:[1,0]
	v_pk_mul_f32 v[8:9], v[8:9], v[176:177] op_sel_hi:[1,0]
	v_pk_mul_f32 v[6:7], v[6:7], v[176:177] op_sel_hi:[1,0]
	v_pk_mul_f32 v[4:5], v[4:5], v[176:177] op_sel_hi:[1,0]
	v_pk_mul_f32 v[2:3], v[2:3], v[176:177] op_sel_hi:[1,0]
	v_pk_mul_f32 v[0:1], v[0:1], v[176:177] op_sel_hi:[1,0]
	v_pk_add_f32 v[72:73], v[72:73], 0 op_sel_hi:[1,0]
	v_mfma_f32_32x32x16_bf16 v[16:31], v[132:135], v[68:71], v[16:31]
	v_add_f32_e64 v72, v74, v72
	v_add_f32_e64 v73, v75, v73
	v_exp_f32_e32 v88, v88
	v_pk_add_f32 v[72:73], v[76:77], v[72:73]
	v_exp_f32_e32 v90, v89
	v_exp_f32_e32 v92, v138
	v_exp_f32_e32 v94, v91
	v_exp_f32_e32 v138, v93
	v_mfma_f32_32x32x16_bf16 v[0:15], v[170:173], v[68:71], v[0:15]
	v_exp_f32_e32 v68, v182
	v_exp_f32_e32 v70, v95
	v_pk_add_f32 v[72:73], v[78:79], v[72:73]
	v_mov_b32_e32 v147, v137
	v_exp_f32_e32 v89, v183
	v_exp_f32_e32 v91, v184
	v_exp_f32_e32 v93, v185
	v_exp_f32_e32 v95, v186
	v_exp_f32_e32 v137, v187
	v_exp_f32_e32 v139, v188
	v_exp_f32_e32 v69, v189
	v_exp_f32_e32 v71, v190
	v_pk_add_f32 v[72:73], v[80:81], v[72:73]
	v_cvt_pk_bf16_f32 v64, v88, v90
	v_pk_add_f32 v[72:73], v[82:83], v[72:73]
	v_cvt_pk_bf16_f32 v65, v92, v94
	v_pk_add_f32 v[72:73], v[84:85], v[72:73]
	v_cvt_pk_bf16_f32 v66, v136, v138
	v_cvt_pk_bf16_f32 v67, v68, v70
	v_pk_add_f32 v[72:73], v[86:87], v[72:73]
	s_nop 0
	v_mfma_f32_32x32x16_bf16 v[48:63], v[128:131], v[64:67], v[48:63]
	v_add_f32_e64 v72, v88, v72
	v_add_f32_e64 v73, v89, v73
	v_add_f32_e64 v72, v90, v72
	v_add_f32_e64 v73, v91, v73
	v_mfma_f32_32x32x16_bf16 v[32:47], v[166:169], v[64:67], v[32:47]
	v_cvt_pk_bf16_f32 v64, v89, v91
	v_cvt_pk_bf16_f32 v65, v93, v95
	v_cvt_pk_bf16_f32 v66, v137, v139
	v_cvt_pk_bf16_f32 v67, v69, v71
	s_nop 1
	v_mfma_f32_32x32x16_bf16 v[16:31], v[128:131], v[64:67], v[16:31]
	v_mfma_f32_32x32x16_bf16 v[0:15], v[166:169], v[64:67], v[0:15]
	v_add_f32_e64 v64, v92, v72
	v_add_f32_e64 v65, v93, v73
	v_add_f32_e64 v64, v94, v64
	v_add_f32_e64 v65, v95, v65
	v_add_f32_e64 v64, v136, v64
	v_add_f32_e64 v65, v137, v65
	v_pk_add_f32 v[64:65], v[138:139], v[64:65]
	s_nop 0
	v_pk_add_f32 v[64:65], v[68:69], v[64:65]
	s_nop 0
	v_pk_add_f32 v[64:65], v[70:71], v[64:65]
	s_nop 0
	v_pk_fma_f32 v[152:153], v[152:153], v[174:175], v[64:65]
	s_cbranch_scc0 .LBB0_434
; DI float ssq32(const f32x16& a, const f32x16& b) {
;     float ss = 0.f;
; #pragma unroll
;     for (int i = 0; i < 16; ++i) ss += a[i] * a[i] + b[i] * b[i];
;     return ss + __shfl_xor(ss, 32);
; }
; DI void mixer_phase(const Params& p, unsigned char* ldsraw, int vid) {
;     ...
;                 lsA += __shfl_xor(lsA, 32); lsB += __shfl_xor(lsB, 32);
;                 const float iA = 1.0f / lsA, iB = 1.0f / lsB;
; #pragma unroll
;                 for (int i = 0; i < 16; ++i) { a0[i] *= iA; a1[i] *= iA; b0[i] *= iB; b1[i] *= iB; }
;                 const float sA = ssq32(a0, a1), sB = ssq32(b0, b1);
;                 if (hh == 0) { lf[512 + wid * 32 + r] = sA; lf[640 + wid * 32 + r] = sB; }
	ds_bpermute_b32 v64, v181, v152
	ds_bpermute_b32 v65, v181, v153
	s_waitcnt lgkmcnt(1)
	v_add_f32_e32 v64, v152, v64
	v_div_scale_f32 v66, s[0:1], v64, v64, 1.0
	v_rcp_f32_e32 v67, v66
	v_div_scale_f32 v68, vcc, 1.0, v64, 1.0
	s_waitcnt lgkmcnt(0)
	v_add_f32_e32 v65, v153, v65
	v_fma_f32 v70, -v66, v67, 1.0
	v_fmac_f32_e32 v67, v70, v67
	v_mul_f32_e32 v70, v68, v67
	v_fma_f32 v71, -v66, v70, v68
	v_div_scale_f32 v69, s[0:1], v65, v65, 1.0
	v_fmac_f32_e32 v70, v71, v67
	v_fma_f32 v66, -v66, v70, v68
	v_rcp_f32_e32 v68, v69
	v_div_fmas_f32 v66, v66, v67, v70
	v_div_fixup_f32 v96, v66, v64, 1.0
	v_pk_mul_f32 v[48:49], v[48:49], v[96:97] op_sel_hi:[1,0]
	v_fma_f32 v64, -v69, v68, 1.0
	v_fmac_f32_e32 v68, v64, v68
	v_div_scale_f32 v64, vcc, 1.0, v65, 1.0
	v_mul_f32_e32 v66, v64, v68
	v_fma_f32 v67, -v69, v66, v64
	v_fmac_f32_e32 v66, v67, v68
	v_fma_f32 v64, -v69, v66, v64
	v_div_fmas_f32 v64, v64, v68, v66
	v_div_fixup_f32 v104, v64, v65, 1.0
	v_pk_mul_f32 v[64:65], v[32:33], v[96:97] op_sel_hi:[1,0]
	v_pk_mul_f32 v[94:95], v[0:1], v[104:105] op_sel_hi:[1,0]
	v_pk_mul_f32 v[66:67], v[34:35], v[96:97] op_sel_hi:[1,0]
	v_pk_mul_f32 v[0:1], v[64:65], v[64:65]
	v_pk_mul_f32 v[50:51], v[50:51], v[96:97] op_sel_hi:[1,0]
	v_pk_mul_f32 v[90:91], v[2:3], v[104:105] op_sel_hi:[1,0]
	v_pk_fma_f32 v[0:1], v[48:49], v[48:49], v[0:1]
	v_pk_mul_f32 v[2:3], v[66:67], v[66:67]
	v_pk_mul_f32 v[68:69], v[36:37], v[96:97] op_sel_hi:[1,0]
	v_pk_fma_f32 v[2:3], v[50:51], v[50:51], v[2:3]
	v_add_f32_e32 v0, v0, v1
	v_pk_mul_f32 v[52:53], v[52:53], v[96:97] op_sel_hi:[1,0]
	v_pk_mul_f32 v[88:89], v[4:5], v[104:105] op_sel_hi:[1,0]
	v_pk_mul_f32 v[4:5], v[68:69], v[68:69]
	v_add_f32_e32 v0, v2, v0
	v_pk_mul_f32 v[70:71], v[38:39], v[96:97] op_sel_hi:[1,0]
	v_pk_fma_f32 v[4:5], v[52:53], v[52:53], v[4:5]
	v_add_f32_e32 v0, v3, v0
	v_pk_mul_f32 v[80:81], v[16:17], v[104:105] op_sel_hi:[1,0]
	v_pk_mul_f32 v[54:55], v[54:55], v[96:97] op_sel_hi:[1,0]
	v_pk_mul_f32 v[92:93], v[6:7], v[104:105] op_sel_hi:[1,0]
	v_pk_mul_f32 v[6:7], v[70:71], v[70:71]
	v_add_f32_e32 v0, v4, v0
	v_pk_mul_f32 v[2:3], v[94:95], v[94:95]
	v_pk_mul_f32 v[76:77], v[18:19], v[104:105] op_sel_hi:[1,0]
	v_pk_mul_f32 v[72:73], v[40:41], v[96:97] op_sel_hi:[1,0]
	v_pk_fma_f32 v[6:7], v[54:55], v[54:55], v[6:7]
	v_add_f32_e32 v0, v5, v0
	v_pk_fma_f32 v[2:3], v[80:81], v[80:81], v[2:3]
	v_pk_mul_f32 v[4:5], v[90:91], v[90:91]
	v_pk_mul_f32 v[56:57], v[56:57], v[96:97] op_sel_hi:[1,0]
	v_pk_mul_f32 v[102:103], v[8:9], v[104:105] op_sel_hi:[1,0]
	v_pk_mul_f32 v[8:9], v[72:73], v[72:73]
	v_add_f32_e32 v0, v6, v0
	v_pk_fma_f32 v[4:5], v[76:77], v[76:77], v[4:5]
	v_add_f32_e32 v2, v2, v3
	v_pk_mul_f32 v[74:75], v[20:21], v[104:105] op_sel_hi:[1,0]
	v_pk_mul_f32 v[40:41], v[58:59], v[96:97] op_sel_hi:[1,0]
	v_pk_mul_f32 v[58:59], v[42:43], v[96:97] op_sel_hi:[1,0]
	v_pk_fma_f32 v[8:9], v[56:57], v[56:57], v[8:9]
	v_add_f32_e32 v0, v7, v0
	v_pk_mul_f32 v[6:7], v[88:89], v[88:89]
	v_add_f32_e32 v2, v4, v2
	v_pk_mul_f32 v[100:101], v[10:11], v[104:105] op_sel_hi:[1,0]
	v_pk_mul_f32 v[10:11], v[58:59], v[58:59]
	v_add_f32_e32 v0, v8, v0
	v_pk_fma_f32 v[6:7], v[74:75], v[74:75], v[6:7]
	v_add_f32_e32 v2, v5, v2
	v_pk_mul_f32 v[78:79], v[22:23], v[104:105] op_sel_hi:[1,0]
	v_pk_mul_f32 v[42:43], v[60:61], v[96:97] op_sel_hi:[1,0]
	v_pk_mul_f32 v[60:61], v[44:45], v[96:97] op_sel_hi:[1,0]
	v_pk_fma_f32 v[10:11], v[40:41], v[40:41], v[10:11]
	v_add_f32_e32 v0, v9, v0
	v_pk_mul_f32 v[8:9], v[92:93], v[92:93]
	v_add_f32_e32 v2, v6, v2
	v_pk_mul_f32 v[98:99], v[12:13], v[104:105] op_sel_hi:[1,0]
	v_pk_mul_f32 v[12:13], v[60:61], v[60:61]
	v_add_f32_e32 v0, v10, v0
	v_pk_fma_f32 v[8:9], v[78:79], v[78:79], v[8:9]
	v_add_f32_e32 v2, v7, v2
	v_pk_mul_f32 v[86:87], v[24:25], v[104:105] op_sel_hi:[1,0]
	v_pk_mul_f32 v[46:47], v[46:47], v[96:97] op_sel_hi:[1,0]
	v_pk_fma_f32 v[12:13], v[42:43], v[42:43], v[12:13]
	v_add_f32_e32 v0, v11, v0
	v_pk_mul_f32 v[10:11], v[102:103], v[102:103]
	v_add_f32_e32 v2, v8, v2
	v_pk_mul_f32 v[84:85], v[26:27], v[104:105] op_sel_hi:[1,0]
	v_pk_mul_f32 v[82:83], v[28:29], v[104:105] op_sel_hi:[1,0]
	v_pk_mul_f32 v[44:45], v[62:63], v[96:97] op_sel_hi:[1,0]
	v_pk_mul_f32 v[62:63], v[30:31], v[104:105] op_sel_hi:[1,0]
	v_pk_mul_f32 v[104:105], v[14:15], v[104:105] op_sel_hi:[1,0]
	v_pk_mul_f32 v[14:15], v[46:47], v[46:47]
	v_add_f32_e32 v0, v12, v0
	v_pk_fma_f32 v[10:11], v[86:87], v[86:87], v[10:11]
	v_add_f32_e32 v2, v9, v2
	v_pk_fma_f32 v[14:15], v[44:45], v[44:45], v[14:15]
	v_add_f32_e32 v0, v13, v0
	v_pk_mul_f32 v[12:13], v[100:101], v[100:101]
	v_add_f32_e32 v2, v10, v2
	v_add_f32_e32 v0, v14, v0
	v_pk_fma_f32 v[12:13], v[84:85], v[84:85], v[12:13]
	v_add_f32_e32 v2, v11, v2
	v_add_f32_e32 v0, v15, v0
	v_pk_mul_f32 v[14:15], v[98:99], v[98:99]
	v_add_f32_e32 v2, v12, v2
	v_pk_fma_f32 v[14:15], v[82:83], v[82:83], v[14:15]
	v_add_f32_e32 v2, v13, v2
	v_pk_mul_f32 v[16:17], v[104:105], v[104:105]
	v_add_f32_e32 v2, v14, v2
	v_pk_fma_f32 v[16:17], v[62:63], v[62:63], v[16:17]
	v_add_f32_e32 v2, v15, v2
	v_add_f32_e32 v2, v16, v2
	v_add_f32_e32 v2, v17, v2
	ds_bpermute_b32 v1, v181, v0
	ds_bpermute_b32 v3, v181, v2
	s_and_saveexec_b64 s[0:1], s[4:5]
	s_cbranch_execz .LBB0_437
	v_lshl_add_u32 v4, v205, 2, s92
	s_waitcnt lgkmcnt(1)
	v_add_f32_e32 v0, v0, v1
	s_waitcnt lgkmcnt(0)
	v_add_f32_e32 v1, v2, v3
	ds_write2st64_b32 v4, v0, v1 offset0:8 offset1:10

; template <int PH> __global__ void __launch_bounds__(512, 2) fwd(Params p) {
;     ...
;     if (PH == 4) finalnorm_phase(p);
; }
.LBB0_574:
	s_endpgm
	.p2alignl	8, 3212836864

; template <int PH> __global__ void __launch_bounds__(512, 2) fwd(Params p) {
;     extern __shared__ __attribute__((aligned(16))) unsigned char lds[];
	.amdhsa_kernel _Z3fwdILin1EEv6Params
		.amdhsa_group_segment_fixed_size 0
		.amdhsa_private_segment_fixed_size 0
		.amdhsa_kernarg_size 376
		.amdhsa_user_sgpr_count 2
		.amdhsa_user_sgpr_dispatch_ptr 0
		.amdhsa_user_sgpr_queue_ptr 0
		.amdhsa_user_sgpr_kernarg_segment_ptr 1
		.amdhsa_user_sgpr_dispatch_id 0
		.amdhsa_user_sgpr_kernarg_preload_length 0
		.amdhsa_user_sgpr_kernarg_preload_offset 0
		.amdhsa_user_sgpr_private_segment_size 0
		.amdhsa_uses_dynamic_stack 0
		.amdhsa_enable_private_segment 0
		.amdhsa_system_sgpr_workgroup_id_x 1
		.amdhsa_system_sgpr_workgroup_id_y 0
		.amdhsa_system_sgpr_workgroup_id_z 0
		.amdhsa_system_sgpr_workgroup_info 0
		.amdhsa_system_vgpr_workitem_id 2
		.amdhsa_next_free_vgpr 256
		.amdhsa_next_free_sgpr 100
		.amdhsa_accum_offset 256
		.amdhsa_reserve_vcc 1
		.amdhsa_float_round_mode_32 0
		.amdhsa_float_round_mode_16_64 0
		.amdhsa_float_denorm_mode_32 3
		.amdhsa_float_denorm_mode_16_64 3
		.amdhsa_dx10_clamp 1
		.amdhsa_ieee_mode 1
		.amdhsa_fp16_overflow 0
		.amdhsa_tg_split 0
		.amdhsa_exception_fp_ieee_invalid_op 0
		.amdhsa_exception_fp_denorm_src 0
		.amdhsa_exception_fp_ieee_div_zero 0
		.amdhsa_exception_fp_ieee_overflow 0
		.amdhsa_exception_fp_ieee_underflow 0
		.amdhsa_exception_fp_ieee_inexact 0
		.amdhsa_exception_int_div_zero 0
	.end_amdhsa_kernel

; template <class Epi, class Sched, bool ALIGN_EPI = false, bool SP2 = true>
; DI void gemm_phase(LAS unsigned char* lds, const Gemm g, const Sched& S, const Epi& E, f32x4 (&acc)[2][2][4][2]) {
;     ...
;     for (;;) {
;         const bool has_next = S.next(ui + 1, nxt);
;         const char* nA = has_next ? (const char*)g.A + (size_t)nxt.pm * tstep : cA; const char* nB = has_next ? (const char*)g.Bt + (size_t)nxt.pn * tstep : cB;
;         for (int t = 0; t < nt; t += 2) {
.LBB2_220:
	s_add_i32 s40, s14, -4
	s_mov_b32 s10, s4
	s_mov_b32 s4, s5
	s_mov_b32 s41, s5
	s_cbranch_execz .LBB2_12
	s_branch .LBB2_13
	.p2alignl	8, 3212836864

; template <int PH> __global__ void __launch_bounds__(512, 2) fwd(Params p) {
;     extern __shared__ __attribute__((aligned(16))) unsigned char lds[];
amdhsa.kernels:
  - .agpr_count:     0
    .args:
      - .offset:         0
        .size:           120
        .value_kind:     by_value
      - .offset:         120
        .size:           4
        .value_kind:     hidden_block_count_x
      - .offset:         124
        .size:           4
        .value_kind:     hidden_block_count_y
      - .offset:         128
        .size:           4
        .value_kind:     hidden_block_count_z
      - .offset:         132
        .size:           2
        .value_kind:     hidden_group_size_x
      - .offset:         134
        .size:           2
        .value_kind:     hidden_group_size_y
      - .offset:         136
        .size:           2
        .value_kind:     hidden_group_size_z
      - .offset:         138
        .size:           2
        .value_kind:     hidden_remainder_x
      - .offset:         140
        .size:           2
        .value_kind:     hidden_remainder_y
      - .offset:         142
        .size:           2
        .value_kind:     hidden_remainder_z
      - .offset:         160
        .size:           8
        .value_kind:     hidden_global_offset_x
      - .offset:         168
        .size:           8
        .value_kind:     hidden_global_offset_y
      - .offset:         176
        .size:           8
        .value_kind:     hidden_global_offset_z
      - .offset:         184
        .size:           2
        .value_kind:     hidden_grid_dims
      - .offset:         208
        .size:           8
        .value_kind:     hidden_multigrid_sync_arg
      - .offset:         240
        .size:           4
        .value_kind:     hidden_dynamic_lds_size
    .group_segment_fixed_size: 0
    .kernarg_segment_align: 8
    .kernarg_segment_size: 376
    .language:       OpenCL C
    .language_version:
      - 2
      - 0
    .max_flat_workgroup_size: 512
    .name:           _Z3fwdILin1EEv6Params
    .private_segment_fixed_size: 0
    .sgpr_count:     106
    .sgpr_spill_count: 4
    .symbol:         _Z3fwdILin1EEv6Params.kd
    .uniform_work_group_size: 1
    .uses_dynamic_stack: false
    .vgpr_count:     256
    .vgpr_spill_count: 0
    .wavefront_size: 64
  - .agpr_count:     0
    .args:
      - .offset:         0
        .size:           120
        .value_kind:     by_value
      - .offset:         120
        .size:           4
        .value_kind:     hidden_block_count_x
      - .offset:         124
        .size:           4
        .value_kind:     hidden_block_count_y
      - .offset:         128
        .size:           4
        .value_kind:     hidden_block_count_z
      - .offset:         132
        .size:           2
        .value_kind:     hidden_group_size_x
      - .offset:         134
        .size:           2
        .value_kind:     hidden_group_size_y
      - .offset:         136
        .size:           2
        .value_kind:     hidden_group_size_z
      - .offset:         138
        .size:           2
        .value_kind:     hidden_remainder_x
      - .offset:         140
        .size:           2
        .value_kind:     hidden_remainder_y
      - .offset:         142
        .size:           2
        .value_kind:     hidden_remainder_z
      - .offset:         160
        .size:           8
        .value_kind:     hidden_global_offset_x
      - .offset:         168
        .size:           8
        .value_kind:     hidden_global_offset_y
      - .offset:         176
        .size:           8
        .value_kind:     hidden_global_offset_z
      - .offset:         184
        .size:           2
        .value_kind:     hidden_grid_dims
      - .offset:         240
        .size:           4
        .value_kind:     hidden_dynamic_lds_size
    .group_segment_fixed_size: 0
    .kernarg_segment_align: 8
    .kernarg_segment_size: 376
    .language:       OpenCL C
    .language_version:
      - 2
      - 0
    .max_flat_workgroup_size: 512
    .name:           _Z3fwdILi0EEv6Params
    .private_segment_fixed_size: 0
    .sgpr_count:     59
    .sgpr_spill_count: 0
    .symbol:         _Z3fwdILi0EEv6Params.kd
    .uniform_work_group_size: 1
    .uses_dynamic_stack: false
    .vgpr_count:     76
    .vgpr_spill_count: 0
    .wavefront_size: 64
  - .agpr_count:     0
    .args:
      - .offset:         0
        .size:           120
        .value_kind:     by_value
      - .offset:         120
        .size:           4
        .value_kind:     hidden_block_count_x
      - .offset:         124
        .size:           4
        .value_kind:     hidden_block_count_y
      - .offset:         128
        .size:           4
        .value_kind:     hidden_block_count_z
      - .offset:         132
        .size:           2
        .value_kind:     hidden_group_size_x
      - .offset:         134
        .size:           2
        .value_kind:     hidden_group_size_y
      - .offset:         136
        .size:           2
        .value_kind:     hidden_group_size_z
      - .offset:         138
        .size:           2
        .value_kind:     hidden_remainder_x
      - .offset:         140
        .size:           2
        .value_kind:     hidden_remainder_y
      - .offset:         142
        .size:           2
        .value_kind:     hidden_remainder_z
      - .offset:         160
        .size:           8
        .value_kind:     hidden_global_offset_x
      - .offset:         168
        .size:           8
        .value_kind:     hidden_global_offset_y
      - .offset:         176
        .size:           8
        .value_kind:     hidden_global_offset_z
      - .offset:         184
        .size:           2
        .value_kind:     hidden_grid_dims
      - .offset:         240
        .size:           4
        .value_kind:     hidden_dynamic_lds_size
    .group_segment_fixed_size: 0
    .kernarg_segment_align: 8
    .kernarg_segment_size: 376
    .language:       OpenCL C
    .language_version:
      - 2
      - 0
    .max_flat_workgroup_size: 512
    .name:           _Z3fwdILi1EEv6Params
    .private_segment_fixed_size: 0
    .sgpr_count:     70
    .sgpr_spill_count: 0
    .symbol:         _Z3fwdILi1EEv6Params.kd
    .uniform_work_group_size: 1
    .uses_dynamic_stack: false
    .vgpr_count:     230
    .vgpr_spill_count: 0
    .wavefront_size: 64
; template <int PH> __global__ void __launch_bounds__(512, 2) fwd(Params p) {
;     extern __shared__ __attribute__((aligned(16))) unsigned char lds[];
  - .agpr_count:     0
    .args:
      - .offset:         0
        .size:           120
        .value_kind:     by_value
      - .offset:         120
        .size:           4
        .value_kind:     hidden_block_count_x
      - .offset:         124
        .size:           4
        .value_kind:     hidden_block_count_y
      - .offset:         128
        .size:           4
        .value_kind:     hidden_block_count_z
      - .offset:         132
        .size:           2
        .value_kind:     hidden_group_size_x
      - .offset:         134
        .size:           2
        .value_kind:     hidden_group_size_y
      - .offset:         136
        .size:           2
        .value_kind:     hidden_group_size_z
      - .offset:         138
        .size:           2
        .value_kind:     hidden_remainder_x
      - .offset:         140
        .size:           2
        .value_kind:     hidden_remainder_y
      - .offset:         142
        .size:           2
        .value_kind:     hidden_remainder_z
      - .offset:         160
        .size:           8
        .value_kind:     hidden_global_offset_x
      - .offset:         168
        .size:           8
        .value_kind:     hidden_global_offset_y
      - .offset:         176
        .size:           8
        .value_kind:     hidden_global_offset_z
      - .offset:         184
        .size:           2
        .value_kind:     hidden_grid_dims
      - .offset:         240
        .size:           4
        .value_kind:     hidden_dynamic_lds_size
    .group_segment_fixed_size: 0
    .kernarg_segment_align: 8
    .kernarg_segment_size: 376
    .language:       OpenCL C
    .language_version:
      - 2
      - 0
    .max_flat_workgroup_size: 512
    .name:           _Z3fwdILi2EEv6Params
    .private_segment_fixed_size: 0
    .sgpr_count:     106
    .sgpr_spill_count: 0
    .symbol:         _Z3fwdILi2EEv6Params.kd
    .uniform_work_group_size: 1
    .uses_dynamic_stack: false
    .vgpr_count:     230
    .vgpr_spill_count: 0
    .wavefront_size: 64
  - .agpr_count:     0
    .args:
      - .offset:         0
        .size:           120
        .value_kind:     by_value
      - .offset:         120
        .size:           4
        .value_kind:     hidden_block_count_x
      - .offset:         124
        .size:           4
        .value_kind:     hidden_block_count_y
      - .offset:         128
        .size:           4
        .value_kind:     hidden_block_count_z
      - .offset:         132
        .size:           2
        .value_kind:     hidden_group_size_x
      - .offset:         134
        .size:           2
        .value_kind:     hidden_group_size_y
      - .offset:         136
        .size:           2
        .value_kind:     hidden_group_size_z
      - .offset:         138
        .size:           2
        .value_kind:     hidden_remainder_x
      - .offset:         140
        .size:           2
        .value_kind:     hidden_remainder_y
      - .offset:         142
        .size:           2
        .value_kind:     hidden_remainder_z
      - .offset:         160
        .size:           8
        .value_kind:     hidden_global_offset_x
      - .offset:         168
        .size:           8
        .value_kind:     hidden_global_offset_y
      - .offset:         176
        .size:           8
        .value_kind:     hidden_global_offset_z
      - .offset:         184
        .size:           2
        .value_kind:     hidden_grid_dims
      - .offset:         240
        .size:           4
        .value_kind:     hidden_dynamic_lds_size
    .group_segment_fixed_size: 0
    .kernarg_segment_align: 8
    .kernarg_segment_size: 376
    .language:       OpenCL C
    .language_version:
      - 2
      - 0
    .max_flat_workgroup_size: 512
    .name:           _Z3fwdILi3EEv6Params
    .private_segment_fixed_size: 0
    .sgpr_count:     72
    .sgpr_spill_count: 0
    .symbol:         _Z3fwdILi3EEv6Params.kd
    .uniform_work_group_size: 1
    .uses_dynamic_stack: false
    .vgpr_count:     220
    .vgpr_spill_count: 0
    .wavefront_size: 64
  - .agpr_count:     0
    .args:
      - .offset:         0
        .size:           120
        .value_kind:     by_value
      - .offset:         120
        .size:           4
        .value_kind:     hidden_block_count_x
      - .offset:         124
        .size:           4
        .value_kind:     hidden_block_count_y
      - .offset:         128
        .size:           4
        .value_kind:     hidden_block_count_z
      - .offset:         132
        .size:           2
        .value_kind:     hidden_group_size_x
      - .offset:         134
        .size:           2
        .value_kind:     hidden_group_size_y
      - .offset:         136
        .size:           2
        .value_kind:     hidden_group_size_z
      - .offset:         138
        .size:           2
        .value_kind:     hidden_remainder_x
      - .offset:         140
        .size:           2
        .value_kind:     hidden_remainder_y
      - .offset:         142
        .size:           2
        .value_kind:     hidden_remainder_z
      - .offset:         160
        .size:           8
        .value_kind:     hidden_global_offset_x
      - .offset:         168
        .size:           8
        .value_kind:     hidden_global_offset_y
      - .offset:         176
        .size:           8
        .value_kind:     hidden_global_offset_z
      - .offset:         184
        .size:           2
        .value_kind:     hidden_grid_dims
    .group_segment_fixed_size: 0
    .kernarg_segment_align: 8
    .kernarg_segment_size: 376
    .language:       OpenCL C
    .language_version:
      - 2
      - 0
    .max_flat_workgroup_size: 512
    .name:           _Z3fwdILi4EEv6Params
    .private_segment_fixed_size: 0
    .sgpr_count:     18
    .sgpr_spill_count: 0
    .symbol:         _Z3fwdILi4EEv6Params.kd
    .uniform_work_group_size: 1
    .uses_dynamic_stack: false
    .vgpr_count:     24
    .vgpr_spill_count: 0
    .wavefront_size: 64
